# dilated units: rare rescale blocks of the left/right tile moved out of line (common path falls through)
# speedup vs baseline: 1.0027x; 1.0027x over previous
.LBB0_514:
	v_add_u32_e32 v32, 64, v208
	v_cvt_f32_i32_e32 v63, v32
	ds_read_b128 v[200:203], v223
	ds_read_b128 v[204:207], v223 offset:4096
	v_add_f32_e32 v33, 0xc2000000, v63
	v_fma_f32 v32, -v186, |v63|, -v188
	v_cmp_ngt_f32_e64 vcc, |v63|, s50
	v_fma_f32 v34, -v186, |v33|, -v188
	v_add_f32_e32 v62, 0xc2580000, v63
	v_cndmask_b32_e32 v32, v227, v32, vcc
	v_cmp_ngt_f32_e64 vcc, |v33|, s50
	v_add_f32_e32 v33, -1.0, v63
	v_fma_f32 v35, -v186, |v33|, -v188
	v_cndmask_b32_e32 v48, v227, v34, vcc
	v_add_f32_e32 v34, 0xc2040000, v63
	v_cmp_ngt_f32_e64 vcc, |v33|, s50
	v_fma_f32 v36, -v186, |v34|, -v188
	s_nop 0
	v_cndmask_b32_e32 v33, v227, v35, vcc
	v_cmp_ngt_f32_e64 vcc, |v34|, s50
	v_add_f32_e32 v34, -2.0, v63
	v_add_f32_e32 v35, 0xc2080000, v63
	v_cndmask_b32_e32 v49, v227, v36, vcc
	v_fma_f32 v36, -v186, |v34|, -v188
	v_cmp_ngt_f32_e64 vcc, |v34|, s50
	v_fma_f32 v37, -v186, |v35|, -v188
	s_nop 0
	v_cndmask_b32_e32 v34, v227, v36, vcc
	v_cmp_ngt_f32_e64 vcc, |v35|, s50
	v_add_f32_e32 v35, 0xc0400000, v63
	v_add_f32_e32 v36, 0xc20c0000, v63
	v_cndmask_b32_e32 v50, v227, v37, vcc
	v_fma_f32 v37, -v186, |v35|, -v188
	v_cmp_ngt_f32_e64 vcc, |v35|, s50
	v_fma_f32 v38, -v186, |v36|, -v188
	s_nop 0
	v_cndmask_b32_e32 v35, v227, v37, vcc
	v_cmp_ngt_f32_e64 vcc, |v36|, s50
	v_add_f32_e32 v36, -4.0, v63
	v_add_f32_e32 v37, 0xc2100000, v63
	v_cndmask_b32_e32 v51, v227, v38, vcc
	v_fma_f32 v38, -v186, |v36|, -v188
	v_cmp_ngt_f32_e64 vcc, |v36|, s50
	v_fma_f32 v39, -v186, |v37|, -v188
	s_nop 0
	v_cndmask_b32_e32 v36, v227, v38, vcc
	v_cmp_ngt_f32_e64 vcc, |v37|, s50
	v_add_f32_e32 v37, 0xc0a00000, v63
	v_add_f32_e32 v38, 0xc2140000, v63
	v_cndmask_b32_e32 v52, v227, v39, vcc
	v_fma_f32 v39, -v186, |v37|, -v188
	v_cmp_ngt_f32_e64 vcc, |v37|, s50
	v_fma_f32 v40, -v186, |v38|, -v188
	s_nop 0
	v_cndmask_b32_e32 v37, v227, v39, vcc
	v_cmp_ngt_f32_e64 vcc, |v38|, s50
	v_add_f32_e32 v38, 0xc0c00000, v63
	v_add_f32_e32 v39, 0xc2180000, v63
	v_cndmask_b32_e32 v53, v227, v40, vcc
	v_fma_f32 v40, -v186, |v38|, -v188
	v_cmp_ngt_f32_e64 vcc, |v38|, s50
	v_fma_f32 v41, -v186, |v39|, -v188
	s_nop 0
	v_cndmask_b32_e32 v38, v227, v40, vcc
	v_cmp_ngt_f32_e64 vcc, |v39|, s50
	v_add_f32_e32 v39, 0xc0e00000, v63
	v_add_f32_e32 v40, 0xc21c0000, v63
	v_cndmask_b32_e32 v54, v227, v41, vcc
	v_fma_f32 v41, -v186, |v39|, -v188
	v_cmp_ngt_f32_e64 vcc, |v39|, s50
	v_fma_f32 v42, -v186, |v40|, -v188
	s_nop 0
	v_cndmask_b32_e32 v39, v227, v41, vcc
	v_cmp_ngt_f32_e64 vcc, |v40|, s50
	v_add_f32_e32 v40, 0xc1800000, v63
	v_add_f32_e32 v41, 0xc2400000, v63
	v_cndmask_b32_e32 v55, v227, v42, vcc
	v_fma_f32 v42, -v186, |v40|, -v188
	v_cmp_ngt_f32_e64 vcc, |v40|, s50
	v_fma_f32 v43, -v186, |v41|, -v188
	s_nop 0
	v_cndmask_b32_e32 v40, v227, v42, vcc
	v_cmp_ngt_f32_e64 vcc, |v41|, s50
	v_add_f32_e32 v41, 0xc1880000, v63
	v_add_f32_e32 v42, 0xc2440000, v63
	v_cndmask_b32_e32 v56, v227, v43, vcc
	v_fma_f32 v43, -v186, |v41|, -v188
	v_cmp_ngt_f32_e64 vcc, |v41|, s50
	v_fma_f32 v44, -v186, |v42|, -v188
	s_nop 0
	v_cndmask_b32_e32 v41, v227, v43, vcc
	v_cmp_ngt_f32_e64 vcc, |v42|, s50
	v_add_f32_e32 v42, 0xc1900000, v63
	v_add_f32_e32 v43, 0xc2480000, v63
	v_cndmask_b32_e32 v57, v227, v44, vcc
	v_fma_f32 v44, -v186, |v42|, -v188
	v_cmp_ngt_f32_e64 vcc, |v42|, s50
	v_fma_f32 v45, -v186, |v43|, -v188
	s_nop 0
	v_cndmask_b32_e32 v42, v227, v44, vcc
	v_cmp_ngt_f32_e64 vcc, |v43|, s50
	v_add_f32_e32 v43, 0xc1980000, v63
	v_add_f32_e32 v44, 0xc24c0000, v63
	v_cndmask_b32_e32 v58, v227, v45, vcc
	v_fma_f32 v45, -v186, |v43|, -v188
	v_cmp_ngt_f32_e64 vcc, |v43|, s50
	v_fma_f32 v46, -v186, |v44|, -v188
	s_nop 0
	v_cndmask_b32_e32 v43, v227, v45, vcc
	v_cmp_ngt_f32_e64 vcc, |v44|, s50
	v_add_f32_e32 v44, 0xc1a00000, v63
	v_add_f32_e32 v45, 0xc2500000, v63
	v_cndmask_b32_e32 v59, v227, v46, vcc
	v_fma_f32 v46, -v186, |v44|, -v188
	v_cmp_ngt_f32_e64 vcc, |v44|, s50
	v_fma_f32 v47, -v186, |v45|, -v188
	s_nop 0
	v_cndmask_b32_e32 v44, v227, v46, vcc
	v_cmp_ngt_f32_e64 vcc, |v45|, s50
	v_add_f32_e32 v45, 0xc1a80000, v63
	v_add_f32_e32 v46, 0xc2540000, v63
	v_cndmask_b32_e32 v60, v227, v47, vcc
	v_fma_f32 v47, -v186, |v45|, -v188
	v_cmp_ngt_f32_e64 vcc, |v45|, s50
	v_fma_f32 v61, -v186, |v46|, -v188
	s_nop 0
	v_cndmask_b32_e32 v45, v227, v47, vcc
	v_cmp_ngt_f32_e64 vcc, |v46|, s50
	v_add_f32_e32 v46, 0xc1b00000, v63
	v_fma_f32 v47, -v186, |v46|, -v188
	v_cndmask_b32_e32 v61, v227, v61, vcc
	v_cmp_ngt_f32_e64 vcc, |v46|, s50
	s_nop 1
	v_cndmask_b32_e32 v46, v227, v47, vcc
	v_add_f32_e32 v47, 0xc1b80000, v63
	v_fma_f32 v185, -v186, |v47|, -v188
	v_cmp_ngt_f32_e64 vcc, |v47|, s50
	v_add_f32_e32 v63, 0xc25c0000, v63
	s_nop 0
	v_cndmask_b32_e32 v47, v227, v185, vcc
	v_fma_f32 v185, -v186, |v62|, -v188
	v_cmp_ngt_f32_e64 vcc, |v62|, s50
	s_waitcnt lgkmcnt(1)
	v_mfma_f32_32x32x16_bf16 v[32:47], v[200:203], v[136:139], v[32:47]
	v_cndmask_b32_e32 v62, v227, v185, vcc
	v_fma_f32 v185, -v186, |v63|, -v188
	v_cmp_ngt_f32_e64 vcc, |v63|, s50
	s_nop 1
	v_cndmask_b32_e32 v63, v227, v185, vcc
	s_waitcnt lgkmcnt(0)
	s_nop 0
	v_mfma_f32_32x32x16_bf16 v[48:63], v[204:207], v[136:139], v[48:63]
	ds_read_b128 v[200:203], v224
	ds_read_b128 v[204:207], v224 offset:4096
	s_waitcnt lgkmcnt(1)
	v_mfma_f32_32x32x16_bf16 v[32:47], v[200:203], v[132:135], v[32:47]
	s_waitcnt lgkmcnt(0)
	v_mfma_f32_32x32x16_bf16 v[48:63], v[204:207], v[132:135], v[48:63]
	ds_read_b128 v[200:203], v225
	ds_read_b128 v[204:207], v225 offset:4096
	s_waitcnt lgkmcnt(1)
	v_mfma_f32_32x32x16_bf16 v[32:47], v[200:203], v[128:131], v[32:47]
	s_waitcnt lgkmcnt(0)
	v_mfma_f32_32x32x16_bf16 v[48:63], v[204:207], v[128:131], v[48:63]
	ds_read_b128 v[200:203], v226
	ds_read_b128 v[204:207], v226 offset:4096
	s_waitcnt lgkmcnt(1)
	v_mfma_f32_32x32x16_bf16 v[32:47], v[200:203], v[124:127], v[32:47]
	s_waitcnt lgkmcnt(0)
	v_mfma_f32_32x32x16_bf16 v[48:63], v[204:207], v[124:127], v[48:63]
	s_nop 9
	v_max_f32_e32 v185, v33, v49
	v_max_f32_e32 v200, v34, v50
	v_max3_f32 v185, v32, v48, v185
	v_max_f32_e32 v201, v35, v51
	v_max3_f32 v185, v185, v200, v201
	v_max_f32_e32 v200, v36, v52
	v_max_f32_e32 v201, v37, v53
	v_max3_f32 v185, v185, v200, v201
	v_max_f32_e32 v200, v38, v54
	v_max_f32_e32 v201, v39, v55
	v_max3_f32 v185, v185, v200, v201
	v_max_f32_e32 v200, v40, v56
	v_max_f32_e32 v201, v41, v57
	v_max3_f32 v185, v185, v200, v201
	v_max_f32_e32 v200, v42, v58
	v_max_f32_e32 v201, v43, v59
	v_max3_f32 v185, v185, v200, v201
	v_max_f32_e32 v200, v44, v60
	v_max_f32_e32 v201, v45, v61
	v_max3_f32 v185, v185, v200, v201
	v_max_f32_e32 v200, v46, v62
	v_max_f32_e32 v201, v47, v63
	v_max3_f32 v185, v185, v200, v201
	v_mov_b32_e32 v200, v185
	s_nop 1
	v_permlane32_swap_b32 v185, v200
	s_nop 1
	s_nop 0
	v_max_f32_e32 v200, v200, v200
	v_max_f32_e32 v185, v185, v185
	v_max_f32_e32 v185, v185, v200
	v_cmp_lt_f32_e32 vcc, s51, v185
	s_cbranch_vccnz .Ldil_cold515

.LBB0_519:
	v_subrev_u32_e32 v32, s84, v228
	v_cvt_f32_i32_e32 v47, v32
	ds_read_b128 v[200:203], v223
	ds_read_b128 v[204:207], v223 offset:4096
	v_add_f32_e32 v33, 0xc2000000, v47
	v_fma_f32 v32, -v186, |v47|, -v188
	v_cmp_ngt_f32_e64 vcc, |v47|, s50
	v_fma_f32 v34, -v186, |v33|, -v188
	s_nop 0
	v_cndmask_b32_e32 v32, v227, v32, vcc
	v_cmp_ngt_f32_e64 vcc, |v33|, s50
	v_add_f32_e32 v33, -1.0, v47
	v_fma_f32 v35, -v186, |v33|, -v188
	v_cndmask_b32_e32 v48, v227, v34, vcc
	v_add_f32_e32 v34, 0xc2040000, v47
	v_cmp_ngt_f32_e64 vcc, |v33|, s50
	v_fma_f32 v36, -v186, |v34|, -v188
	s_nop 0
	v_cndmask_b32_e32 v33, v227, v35, vcc
	v_cmp_ngt_f32_e64 vcc, |v34|, s50
	v_add_f32_e32 v34, -2.0, v47
	v_add_f32_e32 v35, 0xc2080000, v47
	v_cndmask_b32_e32 v49, v227, v36, vcc
	v_fma_f32 v36, -v186, |v34|, -v188
	v_cmp_ngt_f32_e64 vcc, |v34|, s50
	v_fma_f32 v37, -v186, |v35|, -v188
	s_nop 0
	v_cndmask_b32_e32 v34, v227, v36, vcc
	v_cmp_ngt_f32_e64 vcc, |v35|, s50
	v_add_f32_e32 v35, 0xc0400000, v47
	v_add_f32_e32 v36, 0xc20c0000, v47
	v_cndmask_b32_e32 v50, v227, v37, vcc
	v_fma_f32 v37, -v186, |v35|, -v188
	v_cmp_ngt_f32_e64 vcc, |v35|, s50
	v_fma_f32 v38, -v186, |v36|, -v188
	s_nop 0
	v_cndmask_b32_e32 v35, v227, v37, vcc
	v_cmp_ngt_f32_e64 vcc, |v36|, s50
	v_add_f32_e32 v36, -4.0, v47
	v_add_f32_e32 v37, 0xc2100000, v47
	v_cndmask_b32_e32 v51, v227, v38, vcc
	v_fma_f32 v38, -v186, |v36|, -v188
	v_cmp_ngt_f32_e64 vcc, |v36|, s50
	v_fma_f32 v39, -v186, |v37|, -v188
	s_nop 0
	v_cndmask_b32_e32 v36, v227, v38, vcc
	v_cmp_ngt_f32_e64 vcc, |v37|, s50
	v_add_f32_e32 v37, 0xc0a00000, v47
	v_add_f32_e32 v38, 0xc2140000, v47
	v_cndmask_b32_e32 v52, v227, v39, vcc
	v_fma_f32 v39, -v186, |v37|, -v188
	v_cmp_ngt_f32_e64 vcc, |v37|, s50
	v_fma_f32 v40, -v186, |v38|, -v188
	s_nop 0
	v_cndmask_b32_e32 v37, v227, v39, vcc
	v_cmp_ngt_f32_e64 vcc, |v38|, s50
	v_add_f32_e32 v38, 0xc0c00000, v47
	v_add_f32_e32 v39, 0xc2180000, v47
	v_cndmask_b32_e32 v53, v227, v40, vcc
	v_fma_f32 v40, -v186, |v38|, -v188
	v_cmp_ngt_f32_e64 vcc, |v38|, s50
	v_fma_f32 v41, -v186, |v39|, -v188
	s_nop 0
	v_cndmask_b32_e32 v38, v227, v40, vcc
	v_cmp_ngt_f32_e64 vcc, |v39|, s50
	v_add_f32_e32 v39, 0xc0e00000, v47
	v_add_f32_e32 v40, 0xc21c0000, v47
	v_cndmask_b32_e32 v54, v227, v41, vcc
	v_fma_f32 v41, -v186, |v39|, -v188
	v_cmp_ngt_f32_e64 vcc, |v39|, s50
	v_fma_f32 v42, -v186, |v40|, -v188
	s_nop 0
	v_cndmask_b32_e32 v39, v227, v41, vcc
	v_cmp_ngt_f32_e64 vcc, |v40|, s50
	v_add_f32_e32 v40, 0xc1800000, v47
	v_add_f32_e32 v41, 0xc2400000, v47
	v_cndmask_b32_e32 v55, v227, v42, vcc
	v_fma_f32 v42, -v186, |v40|, -v188
	v_cmp_ngt_f32_e64 vcc, |v40|, s50
	v_fma_f32 v43, -v186, |v41|, -v188
	s_nop 0
	v_cndmask_b32_e32 v40, v227, v42, vcc
	v_cmp_ngt_f32_e64 vcc, |v41|, s50
	v_add_f32_e32 v41, 0xc1880000, v47
	v_add_f32_e32 v42, 0xc2440000, v47
	v_cndmask_b32_e32 v56, v227, v43, vcc
	v_fma_f32 v43, -v186, |v41|, -v188
	v_cmp_ngt_f32_e64 vcc, |v41|, s50
	v_fma_f32 v44, -v186, |v42|, -v188
	s_nop 0
	v_cndmask_b32_e32 v41, v227, v43, vcc
	v_cmp_ngt_f32_e64 vcc, |v42|, s50
	v_add_f32_e32 v42, 0xc1900000, v47
	v_add_f32_e32 v43, 0xc2480000, v47
	v_cndmask_b32_e32 v57, v227, v44, vcc
	v_fma_f32 v44, -v186, |v42|, -v188
	v_cmp_ngt_f32_e64 vcc, |v42|, s50
	v_fma_f32 v45, -v186, |v43|, -v188
	s_nop 0
	v_cndmask_b32_e32 v42, v227, v44, vcc
	v_cmp_ngt_f32_e64 vcc, |v43|, s50
	v_add_f32_e32 v43, 0xc1980000, v47
	v_add_f32_e32 v44, 0xc24c0000, v47
	v_cndmask_b32_e32 v58, v227, v45, vcc
	v_fma_f32 v45, -v186, |v43|, -v188
	v_cmp_ngt_f32_e64 vcc, |v43|, s50
	v_fma_f32 v46, -v186, |v44|, -v188
	s_nop 0
	v_cndmask_b32_e32 v43, v227, v45, vcc
	v_cmp_ngt_f32_e64 vcc, |v44|, s50
	v_add_f32_e32 v44, 0xc1a00000, v47
	v_add_f32_e32 v45, 0xc2500000, v47
	v_cndmask_b32_e32 v59, v227, v46, vcc
	v_fma_f32 v46, -v186, |v44|, -v188
	v_cmp_ngt_f32_e64 vcc, |v44|, s50
	v_fma_f32 v60, -v186, |v45|, -v188
	s_nop 0
	v_cndmask_b32_e32 v44, v227, v46, vcc
	v_cmp_ngt_f32_e64 vcc, |v45|, s50
	v_add_f32_e32 v45, 0xc1a80000, v47
	v_add_f32_e32 v46, 0xc2540000, v47
	v_cndmask_b32_e32 v60, v227, v60, vcc
	v_fma_f32 v61, -v186, |v45|, -v188
	v_cmp_ngt_f32_e64 vcc, |v45|, s50
	v_fma_f32 v62, -v186, |v46|, -v188
	s_nop 0
	v_cndmask_b32_e32 v45, v227, v61, vcc
	v_cmp_ngt_f32_e64 vcc, |v46|, s50
	v_add_f32_e32 v46, 0xc1b00000, v47
	v_fma_f32 v63, -v186, |v46|, -v188
	v_cndmask_b32_e32 v61, v227, v62, vcc
	v_add_f32_e32 v62, 0xc2580000, v47
	v_cmp_ngt_f32_e64 vcc, |v46|, s50
	v_fma_f32 v185, -v186, |v62|, -v188
	s_nop 0
	v_cndmask_b32_e32 v46, v227, v63, vcc
	v_cmp_ngt_f32_e64 vcc, |v62|, s50
	v_add_f32_e32 v63, 0xc1b80000, v47
	s_nop 0
	v_cndmask_b32_e32 v62, v227, v185, vcc
	v_add_f32_e32 v185, 0xc25c0000, v47
	v_fma_f32 v47, -v186, |v63|, -v188
	v_cmp_ngt_f32_e64 vcc, |v63|, s50
	v_fma_f32 v186, -v186, |v185|, -v188
	s_nop 0
	v_cndmask_b32_e32 v47, v227, v47, vcc
	v_cmp_ngt_f32_e64 vcc, |v185|, s50
	s_waitcnt lgkmcnt(1)
	v_mfma_f32_32x32x16_bf16 v[32:47], v[200:203], v[136:139], v[32:47]
	v_cndmask_b32_e32 v63, v227, v186, vcc
	s_waitcnt lgkmcnt(0)
	s_nop 0
	v_mfma_f32_32x32x16_bf16 v[48:63], v[204:207], v[136:139], v[48:63]
	ds_read_b128 v[136:139], v224
	ds_read_b128 v[200:203], v224 offset:4096
	s_waitcnt lgkmcnt(1)
	v_mfma_f32_32x32x16_bf16 v[32:47], v[136:139], v[132:135], v[32:47]
	s_waitcnt lgkmcnt(0)
	v_mfma_f32_32x32x16_bf16 v[48:63], v[200:203], v[132:135], v[48:63]
	ds_read_b128 v[132:135], v225
	ds_read_b128 v[136:139], v225 offset:4096
	s_waitcnt lgkmcnt(1)
	v_mfma_f32_32x32x16_bf16 v[32:47], v[132:135], v[128:131], v[32:47]
	s_waitcnt lgkmcnt(0)
	v_mfma_f32_32x32x16_bf16 v[48:63], v[136:139], v[128:131], v[48:63]
	ds_read_b128 v[128:131], v226
	ds_read_b128 v[132:135], v226 offset:4096
	s_waitcnt lgkmcnt(1)
	v_mfma_f32_32x32x16_bf16 v[32:47], v[128:131], v[124:127], v[32:47]
	s_waitcnt lgkmcnt(0)
	v_mfma_f32_32x32x16_bf16 v[48:63], v[132:135], v[124:127], v[48:63]
	s_nop 9
	v_max_f32_e32 v124, v33, v49
	v_max_f32_e32 v125, v34, v50
	v_max3_f32 v124, v32, v48, v124
	v_max_f32_e32 v126, v35, v51
	v_max3_f32 v124, v124, v125, v126
	v_max_f32_e32 v125, v36, v52
	v_max_f32_e32 v126, v37, v53
	v_max3_f32 v124, v124, v125, v126
	v_max_f32_e32 v125, v38, v54
	v_max_f32_e32 v126, v39, v55
	v_max3_f32 v124, v124, v125, v126
	v_max_f32_e32 v125, v40, v56
	v_max_f32_e32 v126, v41, v57
	v_max3_f32 v124, v124, v125, v126
	v_max_f32_e32 v125, v42, v58
	v_max_f32_e32 v126, v43, v59
	v_max3_f32 v124, v124, v125, v126
	v_max_f32_e32 v125, v44, v60
	v_max_f32_e32 v126, v45, v61
	v_max3_f32 v124, v124, v125, v126
	v_max_f32_e32 v125, v46, v62
	v_max_f32_e32 v126, v47, v63
	v_max3_f32 v124, v124, v125, v126
	v_mov_b32_e32 v125, v124
	s_nop 1
	v_permlane32_swap_b32 v125, v124
	s_nop 1
	s_nop 0
	v_max_f32_e32 v124, v124, v124
	v_max_f32_e32 v125, v125, v125
	v_max_f32_e32 v124, v125, v124
	v_cmp_lt_f32_e32 vcc, s51, v124
	s_cbranch_vccnz .Ldil_cold520

.Ldil_cold515:
	v_max_f32_e32 v185, v185, v185
	v_max_f32_e32 v200, 0, v185
	v_exp_f32_e64 v202, -v200
	v_add_f32_e32 v188, v188, v200
	v_pk_add_f32 v[32:33], v[32:33], v[200:201] op_sel_hi:[1,0] neg_lo:[0,1] neg_hi:[0,1]
	v_pk_add_f32 v[48:49], v[48:49], v[200:201] op_sel_hi:[1,0] neg_lo:[0,1] neg_hi:[0,1]
	v_pk_add_f32 v[34:35], v[34:35], v[200:201] op_sel_hi:[1,0] neg_lo:[0,1] neg_hi:[0,1]
	v_pk_add_f32 v[50:51], v[50:51], v[200:201] op_sel_hi:[1,0] neg_lo:[0,1] neg_hi:[0,1]
	v_pk_add_f32 v[36:37], v[36:37], v[200:201] op_sel_hi:[1,0] neg_lo:[0,1] neg_hi:[0,1]
	v_pk_add_f32 v[52:53], v[52:53], v[200:201] op_sel_hi:[1,0] neg_lo:[0,1] neg_hi:[0,1]
	v_pk_add_f32 v[38:39], v[38:39], v[200:201] op_sel_hi:[1,0] neg_lo:[0,1] neg_hi:[0,1]
	v_pk_add_f32 v[54:55], v[54:55], v[200:201] op_sel_hi:[1,0] neg_lo:[0,1] neg_hi:[0,1]
	v_pk_add_f32 v[40:41], v[40:41], v[200:201] op_sel_hi:[1,0] neg_lo:[0,1] neg_hi:[0,1]
	v_pk_add_f32 v[56:57], v[56:57], v[200:201] op_sel_hi:[1,0] neg_lo:[0,1] neg_hi:[0,1]
	v_pk_add_f32 v[42:43], v[42:43], v[200:201] op_sel_hi:[1,0] neg_lo:[0,1] neg_hi:[0,1]
	v_pk_add_f32 v[58:59], v[58:59], v[200:201] op_sel_hi:[1,0] neg_lo:[0,1] neg_hi:[0,1]
	v_pk_add_f32 v[44:45], v[44:45], v[200:201] op_sel_hi:[1,0] neg_lo:[0,1] neg_hi:[0,1]
	v_pk_add_f32 v[60:61], v[60:61], v[200:201] op_sel_hi:[1,0] neg_lo:[0,1] neg_hi:[0,1]
	v_pk_add_f32 v[46:47], v[46:47], v[200:201] op_sel_hi:[1,0] neg_lo:[0,1] neg_hi:[0,1]
	v_pk_add_f32 v[62:63], v[62:63], v[200:201] op_sel_hi:[1,0] neg_lo:[0,1] neg_hi:[0,1]
	v_mul_f32_e32 v189, v189, v202
	v_pk_mul_f32 v[30:31], v[30:31], v[202:203] op_sel_hi:[1,0]
	v_pk_mul_f32 v[28:29], v[28:29], v[202:203] op_sel_hi:[1,0]
	v_pk_mul_f32 v[26:27], v[26:27], v[202:203] op_sel_hi:[1,0]
	v_pk_mul_f32 v[24:25], v[24:25], v[202:203] op_sel_hi:[1,0]
	v_pk_mul_f32 v[22:23], v[22:23], v[202:203] op_sel_hi:[1,0]
	v_pk_mul_f32 v[20:21], v[20:21], v[202:203] op_sel_hi:[1,0]
	v_pk_mul_f32 v[18:19], v[18:19], v[202:203] op_sel_hi:[1,0]
	v_pk_mul_f32 v[16:17], v[16:17], v[202:203] op_sel_hi:[1,0]
	v_pk_mul_f32 v[14:15], v[14:15], v[202:203] op_sel_hi:[1,0]
	v_pk_mul_f32 v[12:13], v[12:13], v[202:203] op_sel_hi:[1,0]
	v_pk_mul_f32 v[10:11], v[10:11], v[202:203] op_sel_hi:[1,0]
	v_pk_mul_f32 v[8:9], v[8:9], v[202:203] op_sel_hi:[1,0]
	v_pk_mul_f32 v[6:7], v[6:7], v[202:203] op_sel_hi:[1,0]
	v_pk_mul_f32 v[4:5], v[4:5], v[202:203] op_sel_hi:[1,0]
	v_pk_mul_f32 v[2:3], v[2:3], v[202:203] op_sel_hi:[1,0]
	v_pk_mul_f32 v[0:1], v[0:1], v[202:203] op_sel_hi:[1,0]
	s_branch .LBB0_516
.Ldil_cold520:
	v_max_f32_e32 v124, v124, v124
	v_max_f32_e32 v124, 0, v124
	v_exp_f32_e64 v126, -v124
	v_add_f32_e32 v188, v188, v124
	v_pk_add_f32 v[32:33], v[32:33], v[124:125] op_sel_hi:[1,0] neg_lo:[0,1] neg_hi:[0,1]
	v_pk_add_f32 v[48:49], v[48:49], v[124:125] op_sel_hi:[1,0] neg_lo:[0,1] neg_hi:[0,1]
	v_pk_add_f32 v[34:35], v[34:35], v[124:125] op_sel_hi:[1,0] neg_lo:[0,1] neg_hi:[0,1]
	v_pk_add_f32 v[50:51], v[50:51], v[124:125] op_sel_hi:[1,0] neg_lo:[0,1] neg_hi:[0,1]
	v_pk_add_f32 v[36:37], v[36:37], v[124:125] op_sel_hi:[1,0] neg_lo:[0,1] neg_hi:[0,1]
	v_pk_add_f32 v[52:53], v[52:53], v[124:125] op_sel_hi:[1,0] neg_lo:[0,1] neg_hi:[0,1]
	v_pk_add_f32 v[38:39], v[38:39], v[124:125] op_sel_hi:[1,0] neg_lo:[0,1] neg_hi:[0,1]
	v_pk_add_f32 v[54:55], v[54:55], v[124:125] op_sel_hi:[1,0] neg_lo:[0,1] neg_hi:[0,1]
	v_pk_add_f32 v[40:41], v[40:41], v[124:125] op_sel_hi:[1,0] neg_lo:[0,1] neg_hi:[0,1]
	v_pk_add_f32 v[56:57], v[56:57], v[124:125] op_sel_hi:[1,0] neg_lo:[0,1] neg_hi:[0,1]
	v_pk_add_f32 v[42:43], v[42:43], v[124:125] op_sel_hi:[1,0] neg_lo:[0,1] neg_hi:[0,1]
	v_pk_add_f32 v[58:59], v[58:59], v[124:125] op_sel_hi:[1,0] neg_lo:[0,1] neg_hi:[0,1]
	v_pk_add_f32 v[44:45], v[44:45], v[124:125] op_sel_hi:[1,0] neg_lo:[0,1] neg_hi:[0,1]
	v_pk_add_f32 v[60:61], v[60:61], v[124:125] op_sel_hi:[1,0] neg_lo:[0,1] neg_hi:[0,1]
	v_pk_add_f32 v[46:47], v[46:47], v[124:125] op_sel_hi:[1,0] neg_lo:[0,1] neg_hi:[0,1]
	v_pk_add_f32 v[62:63], v[62:63], v[124:125] op_sel_hi:[1,0] neg_lo:[0,1] neg_hi:[0,1]
	v_mul_f32_e32 v189, v189, v126
	v_pk_mul_f32 v[30:31], v[30:31], v[126:127] op_sel_hi:[1,0]
	v_pk_mul_f32 v[28:29], v[28:29], v[126:127] op_sel_hi:[1,0]
	v_pk_mul_f32 v[26:27], v[26:27], v[126:127] op_sel_hi:[1,0]
	v_pk_mul_f32 v[24:25], v[24:25], v[126:127] op_sel_hi:[1,0]
	v_pk_mul_f32 v[22:23], v[22:23], v[126:127] op_sel_hi:[1,0]
	v_pk_mul_f32 v[20:21], v[20:21], v[126:127] op_sel_hi:[1,0]
	v_pk_mul_f32 v[18:19], v[18:19], v[126:127] op_sel_hi:[1,0]
	v_pk_mul_f32 v[16:17], v[16:17], v[126:127] op_sel_hi:[1,0]
	v_pk_mul_f32 v[14:15], v[14:15], v[126:127] op_sel_hi:[1,0]
	v_pk_mul_f32 v[12:13], v[12:13], v[126:127] op_sel_hi:[1,0]
	v_pk_mul_f32 v[10:11], v[10:11], v[126:127] op_sel_hi:[1,0]
	v_pk_mul_f32 v[8:9], v[8:9], v[126:127] op_sel_hi:[1,0]
	v_pk_mul_f32 v[6:7], v[6:7], v[126:127] op_sel_hi:[1,0]
	v_pk_mul_f32 v[4:5], v[4:5], v[126:127] op_sel_hi:[1,0]
	v_pk_mul_f32 v[2:3], v[2:3], v[126:127] op_sel_hi:[1,0]
	v_pk_mul_f32 v[0:1], v[0:1], v[126:127] op_sel_hi:[1,0]
	s_branch .LBB0_521
